# two V fragment reads hoisted next to the first V read into free VGPRs (LDS op order unchanged)
# baseline (speedup 1.0000x reference)
.LBB0_895:
	ds_read_b128 v[124:127], v201 offset:12288
	ds_read_b128 v[128:131], v201 offset:13312
	ds_read_b128 v[136:139], v201 offset:15360
	ds_read_b128 v[140:143], v201 offset:14336
	ds_read_b128 v[148:151], v201 offset:18432
	ds_read_b128 v[152:155], v201 offset:19456
	ds_read_b128 v[204:207], v201 offset:21504
	ds_read_b128 v[208:211], v201 offset:20480
	s_waitcnt lgkmcnt(7)
	v_mfma_f32_16x16x32_bf16 v[132:135], v[124:127], v[12:15], v[44:47]
	v_exp_f32_e32 v195, v84
	v_exp_f32_e32 v194, v88
	v_mfma_f32_16x16x32_bf16 v[124:127], v[124:127], v[16:19], v[48:51]
	v_exp_f32_e32 v88, v91
	v_exp_f32_e32 v84, v81
	s_waitcnt lgkmcnt(3)
	v_mfma_f32_16x16x32_bf16 v[190:193], v[148:151], v[12:15], v[44:47]
	v_exp_f32_e32 v81, v78
	v_exp_f32_e32 v79, v79
	v_mfma_f32_16x16x32_bf16 v[148:151], v[148:151], v[16:19], v[48:51]
	v_exp_f32_e32 v78, v83
	v_exp_f32_e32 v61, v61
	v_mfma_f32_16x16x32_bf16 v[144:147], v[136:139], v[12:15], v[44:47]
	v_exp_f32_e32 v63, v63
	v_exp_f32_e32 v83, v64
	v_mfma_f32_16x16x32_bf16 v[136:139], v[136:139], v[16:19], v[48:51]
	v_exp_f32_e32 v64, v74
	v_exp_f32_e32 v67, v67
	s_waitcnt lgkmcnt(1)
	v_mfma_f32_16x16x32_bf16 v[212:215], v[204:207], v[12:15], v[44:47]
	v_exp_f32_e32 v250, v90
	v_mfma_f32_16x16x32_bf16 v[204:207], v[204:207], v[16:19], v[48:51]
	v_mfma_f32_16x16x32_bf16 v[132:135], v[128:131], v[4:7], v[132:135]
	v_mfma_f32_16x16x32_bf16 v[124:127], v[128:131], v[20:23], v[124:127]
	ds_read_b128 v[128:131], v201 offset:16384
	ds_read_b128 v[216:219], v201 offset:17408
	v_mfma_f32_16x16x32_bf16 v[220:223], v[152:155], v[20:23], v[148:151]
	v_exp_f32_e32 v249, v85
	v_exp_f32_e32 v248, v89
	v_exp_f32_e32 v251, v86
	ds_read_b128 v[148:151], v201 offset:22528
	ds_read_b128 v[224:227], v201 offset:23552
	s_waitcnt lgkmcnt(3)
	v_mfma_f32_16x16x32_bf16 v[144:147], v[128:131], v[4:7], v[144:147]
	v_exp_f32_e32 v89, v87
	v_exp_f32_e32 v87, v76
	v_mfma_f32_16x16x32_bf16 v[128:131], v[128:131], v[20:23], v[136:139]
	v_exp_f32_e32 v86, v80
	s_waitcnt lgkmcnt(1)
	v_mfma_f32_16x16x32_bf16 v[204:207], v[148:151], v[20:23], v[204:207]
	v_exp_f32_e32 v85, v77
	v_exp_f32_e32 v80, v82
	v_mfma_f32_16x16x32_bf16 v[136:139], v[152:155], v[4:7], v[190:193]
	v_exp_f32_e32 v77, v60
	v_mfma_f32_16x16x32_bf16 v[212:215], v[148:151], v[4:7], v[212:215]
	v_exp_f32_e32 v76, v68
	v_exp_f32_e32 v60, v69
	v_mfma_f32_16x16x32_bf16 v[148:151], v[140:143], v[8:11], v[132:135]
	v_exp_f32_e32 v69, v62
	v_mfma_f32_16x16x32_bf16 v[152:155], v[140:143], v[24:27], v[124:127]
	v_exp_f32_e32 v68, v70
	v_exp_f32_e32 v62, v71
	v_mfma_f32_16x16x32_bf16 v[140:143], v[216:219], v[8:11], v[144:147]
	v_exp_f32_e32 v82, v72
	v_mfma_f32_16x16x32_bf16 v[144:147], v[216:219], v[24:27], v[128:131]
	v_exp_f32_e32 v71, v65
	v_exp_f32_e32 v70, v73
	s_waitcnt lgkmcnt(0)
	v_mfma_f32_16x16x32_bf16 v[128:131], v[224:227], v[24:27], v[204:207]
	v_exp_f32_e32 v65, v66
	ds_read_b128 v[204:207], v200 offset:24576
	ds_read_b128 v[236:239], v200 offset:26624
	ds_read_b128 v[240:243], v200 offset:25600
	v_mfma_f32_16x16x32_bf16 v[132:135], v[208:211], v[8:11], v[136:139]
	v_exp_f32_e32 v66, v75
	v_cvt_pk_bf16_f32 v90, v77, v61
	v_mfma_f32_16x16x32_bf16 v[136:139], v[208:211], v[24:27], v[220:223]
	v_cvt_pk_bf16_f32 v208, v195, v249
	v_cvt_pk_bf16_f32 v209, v251, v89
	v_cvt_pk_bf16_f32 v210, v87, v85
	v_mfma_f32_16x16x32_bf16 v[124:127], v[224:227], v[8:11], v[212:215]
	v_cvt_pk_bf16_f32 v211, v81, v79
	v_cvt_pk_bf16_f32 v212, v194, v248
	v_cvt_pk_bf16_f32 v213, v250, v88
	v_cvt_pk_bf16_f32 v214, v86, v84
	v_cvt_pk_bf16_f32 v215, v80, v78
	s_waitcnt lgkmcnt(2)
	v_mfma_f32_16x16x32_bf16 v[120:123], v[204:207], v[208:211], v[120:123]
	v_cvt_pk_bf16_f32 v91, v69, v63
	v_mfma_f32_16x16x32_bf16 v[104:107], v[204:207], v[212:215], v[104:107]
	ds_read_b128 v[204:207], v200 offset:28672
	ds_read_b128 v[224:227], v200 offset:27648
	s_waitcnt lgkmcnt(3)
	v_mfma_f32_16x16x32_bf16 v[228:231], v[236:239], v[208:211], v[116:119]
	v_mfma_f32_16x16x32_bf16 v[100:103], v[236:239], v[212:215], v[100:103]
	s_nop 1
	ds_read_b128 v[116:119], v200 offset:30720
	ds_read_b128 v[216:219], v200 offset:29696
	s_waitcnt lgkmcnt(3)
	v_mfma_f32_16x16x32_bf16 v[232:235], v[204:207], v[208:211], v[112:115]
	v_mfma_f32_16x16x32_bf16 v[96:99], v[204:207], v[212:215], v[96:99]
	ds_read_b128 v[204:207], v200 offset:31744
	s_waitcnt lgkmcnt(2)
	v_mfma_f32_16x16x32_bf16 v[208:211], v[116:119], v[208:211], v[108:111]
	v_mfma_f32_16x16x32_bf16 v[72:75], v[116:119], v[212:215], v[92:95]
	v_cvt_pk_bf16_f32 v212, v76, v60
	v_cvt_pk_bf16_f32 v213, v68, v62
	v_cvt_pk_bf16_f32 v214, v82, v70
	v_cvt_pk_bf16_f32 v92, v83, v71
	v_cvt_pk_bf16_f32 v93, v65, v67
	v_cvt_pk_bf16_f32 v215, v64, v66
	s_nop 0
	v_mfma_f32_16x16x32_bf16 v[120:123], v[240:243], v[90:93], v[120:123]
	v_mfma_f32_16x16x32_bf16 v[116:119], v[240:243], v[212:215], v[104:107]
	v_max3_f32 v244, v152, v153, v154
	v_max3_f32 v245, v148, v149, v150
	v_mfma_f32_16x16x32_bf16 v[112:115], v[224:227], v[90:93], v[228:231]
	v_max3_f32 v244, v244, v155, v144
	v_max3_f32 v245, v245, v151, v140
	v_mfma_f32_16x16x32_bf16 v[108:111], v[224:227], v[212:215], v[100:103]
	v_max3_f32 v244, v244, v145, v146
	v_max3_f32 v245, v245, v141, v142
	s_waitcnt lgkmcnt(1)
	v_mfma_f32_16x16x32_bf16 v[104:107], v[216:219], v[90:93], v[232:235]
	v_max3_f32 v244, v244, v147, v136
	v_max3_f32 v245, v245, v143, v132
	v_mfma_f32_16x16x32_bf16 v[100:103], v[216:219], v[212:215], v[96:99]
	v_max3_f32 v244, v244, v137, v138
	v_max3_f32 v245, v245, v133, v134
	s_waitcnt lgkmcnt(0)
	v_mfma_f32_16x16x32_bf16 v[92:95], v[204:207], v[90:93], v[208:211]
	v_max3_f32 v244, v244, v139, v128
	v_max3_f32 v245, v245, v135, v124
	v_mfma_f32_16x16x32_bf16 v[96:99], v[204:207], v[212:215], v[72:75]
	v_max3_f32 v244, v244, v129, v130
	v_max3_f32 v245, v245, v125, v126
	s_waitcnt vmcnt(0)
	ds_write_b128 v197, v[52:55]
	s_and_saveexec_b64 s[16:17], s[10:11]
	ds_write_b128 v199, v[28:31]
	s_or_b64 exec, exec, s[16:17]

.LBB0_907:
	ds_read_b128 v[60:63], v201
	ds_read_b128 v[64:67], v201 offset:1024
	ds_read_b128 v[72:75], v201 offset:3072
	ds_read_b128 v[76:79], v201 offset:2048
	ds_read_b128 v[84:87], v201 offset:6144
	ds_read_b128 v[88:91], v201 offset:7168
	ds_read_b128 v[190:193], v201 offset:9216
	ds_read_b128 v[204:207], v201 offset:8192
	s_waitcnt lgkmcnt(7)
	v_mfma_f32_16x16x32_bf16 v[68:71], v[60:63], v[12:15], v[44:47]
	v_exp_f32_e32 v149, v149
	v_exp_f32_e32 v151, v151
	v_mfma_f32_16x16x32_bf16 v[60:63], v[60:63], v[16:19], v[48:51]
	v_exp_f32_e32 v143, v143
	v_exp_f32_e32 v133, v133
	s_waitcnt lgkmcnt(3)
	v_mfma_f32_16x16x32_bf16 v[186:189], v[84:87], v[12:15], v[44:47]
	v_exp_f32_e32 v135, v135
	v_exp_f32_e32 v127, v127
	v_mfma_f32_16x16x32_bf16 v[84:87], v[84:87], v[16:19], v[48:51]
	v_exp_f32_e32 v249, v148
	v_exp_f32_e32 v248, v152
	v_mfma_f32_16x16x32_bf16 v[80:83], v[72:75], v[12:15], v[44:47]
	v_exp_f32_e32 v148, v153
	v_mfma_f32_16x16x32_bf16 v[72:75], v[72:75], v[16:19], v[48:51]
	v_exp_f32_e32 v153, v150
	v_exp_f32_e32 v152, v154
	s_waitcnt lgkmcnt(1)
	v_mfma_f32_16x16x32_bf16 v[208:211], v[190:193], v[12:15], v[44:47]
	v_exp_f32_e32 v150, v155
	v_mfma_f32_16x16x32_bf16 v[190:193], v[190:193], v[16:19], v[48:51]
	v_exp_f32_e32 v155, v141
	v_exp_f32_e32 v154, v145
	v_mfma_f32_16x16x32_bf16 v[68:71], v[64:67], v[4:7], v[68:71]
	v_exp_f32_e32 v145, v142
	v_mfma_f32_16x16x32_bf16 v[60:63], v[64:67], v[20:23], v[60:63]
	v_exp_f32_e32 v142, v147
	ds_read_b128 v[64:67], v201 offset:4096
	ds_read_b128 v[212:215], v201 offset:5120
	v_mfma_f32_16x16x32_bf16 v[216:219], v[88:91], v[20:23], v[84:87]
	v_exp_f32_e32 v141, v132
	v_exp_f32_e32 v132, v137
	v_exp_f32_e32 v251, v140
	ds_read_b128 v[84:87], v201 offset:10240
	ds_read_b128 v[220:223], v201 offset:11264
	s_waitcnt lgkmcnt(3)
	v_mfma_f32_16x16x32_bf16 v[80:83], v[64:67], v[4:7], v[80:83]
	v_exp_f32_e32 v250, v144
	v_mfma_f32_16x16x32_bf16 v[64:67], v[64:67], v[20:23], v[72:75]
	v_exp_f32_e32 v144, v146
	v_exp_f32_e32 v140, v136
	v_mfma_f32_16x16x32_bf16 v[72:75], v[88:91], v[4:7], v[186:189]
	v_exp_f32_e32 v137, v134
	s_waitcnt lgkmcnt(1)
	v_mfma_f32_16x16x32_bf16 v[188:191], v[84:87], v[20:23], v[190:193]
	v_exp_f32_e32 v136, v138
	v_exp_f32_e32 v134, v139
	v_mfma_f32_16x16x32_bf16 v[88:91], v[76:79], v[24:27], v[60:63]
	v_exp_f32_e32 v139, v124
	v_mfma_f32_16x16x32_bf16 v[60:63], v[204:207], v[8:11], v[72:75]
	v_exp_f32_e32 v138, v128
	s_waitcnt lgkmcnt(0)
	v_mfma_f32_16x16x32_bf16 v[72:75], v[220:223], v[24:27], v[188:191]
	v_exp_f32_e32 v147, v125
	ds_read_b128 v[190:193], v200 offset:32768
	ds_read_b128 v[236:239], v200 offset:34816
	ds_read_b128 v[240:243], v200 offset:33792
	v_mfma_f32_16x16x32_bf16 v[208:211], v[84:87], v[4:7], v[208:211]
	v_exp_f32_e32 v146, v129
	v_mfma_f32_16x16x32_bf16 v[84:87], v[76:79], v[8:11], v[68:71]
	v_exp_f32_e32 v125, v126
	v_mfma_f32_16x16x32_bf16 v[76:79], v[212:215], v[8:11], v[80:83]
	v_exp_f32_e32 v124, v130
	v_mfma_f32_16x16x32_bf16 v[80:83], v[212:215], v[24:27], v[64:67]
	v_exp_f32_e32 v126, v131
	v_mfma_f32_16x16x32_bf16 v[68:71], v[204:207], v[24:27], v[216:219]
	v_cvt_pk_bf16_f32 v204, v249, v149
	v_cvt_pk_bf16_f32 v205, v153, v151
	v_mfma_f32_16x16x32_bf16 v[64:67], v[220:223], v[8:11], v[208:211]
	v_cvt_pk_bf16_f32 v206, v251, v155
	v_cvt_pk_bf16_f32 v207, v145, v143
	v_cvt_pk_bf16_f32 v208, v248, v148
	v_cvt_pk_bf16_f32 v209, v152, v150
	v_cvt_pk_bf16_f32 v210, v250, v154
	v_cvt_pk_bf16_f32 v211, v144, v142
	s_waitcnt lgkmcnt(2)
	v_mfma_f32_16x16x32_bf16 v[120:123], v[190:193], v[204:207], v[120:123]
	v_mfma_f32_16x16x32_bf16 v[116:119], v[190:193], v[208:211], v[116:119]
	ds_read_b128 v[190:193], v200 offset:36864
	ds_read_b128 v[220:223], v200 offset:35840
	s_waitcnt lgkmcnt(3)
	v_mfma_f32_16x16x32_bf16 v[112:115], v[236:239], v[204:207], v[112:115]
	v_mfma_f32_16x16x32_bf16 v[108:111], v[236:239], v[208:211], v[108:111]
	ds_read_b128 v[212:215], v200 offset:38912
	ds_read_b128 v[224:227], v200 offset:37888
	ds_read_b128 v[232:235], v200 offset:39936
	s_waitcnt lgkmcnt(4)
	v_mfma_f32_16x16x32_bf16 v[228:231], v[190:193], v[204:207], v[104:107]
	v_mfma_f32_16x16x32_bf16 v[190:193], v[190:193], v[208:211], v[100:103]
	s_waitcnt lgkmcnt(2)
	v_mfma_f32_16x16x32_bf16 v[92:95], v[212:215], v[204:207], v[92:95]
	v_cvt_pk_bf16_f32 v204, v141, v133
	v_cvt_pk_bf16_f32 v205, v137, v135
	v_cvt_pk_bf16_f32 v206, v139, v147
	v_mfma_f32_16x16x32_bf16 v[128:131], v[212:215], v[208:211], v[96:99]
	v_cvt_pk_bf16_f32 v207, v125, v127
	v_cvt_pk_bf16_f32 v208, v140, v132
	v_cvt_pk_bf16_f32 v209, v136, v134
	v_cvt_pk_bf16_f32 v210, v138, v146
	v_cvt_pk_bf16_f32 v211, v124, v126
	v_mfma_f32_16x16x32_bf16 v[120:123], v[240:243], v[204:207], v[120:123]
	s_nop 0
	v_mfma_f32_16x16x32_bf16 v[104:107], v[240:243], v[208:211], v[116:119]
	v_max3_f32 v246, v88, v89, v90
	v_max3_f32 v247, v84, v85, v86
	v_mfma_f32_16x16x32_bf16 v[116:119], v[220:223], v[204:207], v[112:115]
	v_max3_f32 v246, v246, v91, v80
	v_max3_f32 v247, v247, v87, v76
	v_mfma_f32_16x16x32_bf16 v[100:103], v[220:223], v[208:211], v[108:111]
	v_max3_f32 v246, v246, v81, v82
	v_max3_f32 v247, v247, v77, v78
	s_waitcnt lgkmcnt(1)
	v_mfma_f32_16x16x32_bf16 v[112:115], v[224:227], v[204:207], v[228:231]
	v_max3_f32 v246, v246, v83, v68
	v_max3_f32 v247, v247, v79, v60
	v_mfma_f32_16x16x32_bf16 v[96:99], v[224:227], v[208:211], v[190:193]
	v_max3_f32 v246, v246, v69, v70
	v_max3_f32 v247, v247, v61, v62
	s_waitcnt lgkmcnt(0)
	v_mfma_f32_16x16x32_bf16 v[108:111], v[232:235], v[204:207], v[92:95]
	v_max3_f32 v246, v246, v71, v72
	v_max3_f32 v247, v247, v63, v64
	v_mfma_f32_16x16x32_bf16 v[92:95], v[232:235], v[208:211], v[128:131]
	v_max3_f32 v246, v246, v73, v74
	v_max3_f32 v247, v247, v65, v66
	ds_write_b128 v197, v[32:35] offset:12288
	s_and_saveexec_b64 s[16:17], s[10:11]
	ds_write_b128 v199, v[36:39] offset:12288
	s_or_b64 exec, exec, s[16:17]
